# prompt loop: first MFMA of the tile issues immediately (no VALU lead), operands being prefetched across the tile boundary
# baseline (speedup 1.0000x reference)
.LBB0_822:
	s_mov_b32 s5, 0
	s_waitcnt lgkmcnt(2)
	v_mfma_f32_32x32x16_bf16 v[4:19], v[164:167], v[144:147], v[4:19]
	ds_read_b64_tr_b16 v[176:177], v162 offset:29760
	ds_read_b64_tr_b16 v[178:179], v162 offset:31296
	ds_read_b64_tr_b16 v[164:165], v162 offset:32768
	ds_read_b64_tr_b16 v[166:167], v162 offset:34304
	v_exp_f32_e32 v124, v84
	v_exp_f32_e32 v125, v85
	v_exp_f32_e32 v126, v86
	v_add_f32_e32 v224, v124, v125
	v_mfma_f32_32x32x16_bf16 v[20:35], v[168:171], v[144:147], v[20:35]
	ds_read_b64_tr_b16 v[168:169], v162 offset:32832
	ds_read_b64_tr_b16 v[170:171], v162 offset:34368
	v_exp_f32_e32 v127, v87
	v_cvt_pk_bf16_f32 v184, v124, v125
	v_mov_b32_e32 v254, v224
	v_exp_f32_e32 v128, v88
	s_waitcnt lgkmcnt(4)
	v_mfma_f32_32x32x16_bf16 v[4:19], v[172:175], v[140:143], v[4:19]
	ds_read_b64_tr_b16 v[172:173], v162 offset:35840
	ds_read_b64_tr_b16 v[174:175], v162 offset:37376
	v_add_f32_e32 v226, v126, v127
	v_exp_f32_e32 v129, v89
	v_cvt_pk_bf16_f32 v185, v126, v127
	v_add_f32_e32 v254, v254, v226
	v_mfma_f32_32x32x16_bf16 v[20:35], v[176:179], v[140:143], v[20:35]
	ds_read_b64_tr_b16 v[176:177], v162 offset:35904
	ds_read_b64_tr_b16 v[178:179], v162 offset:37440
	v_exp_f32_e32 v130, v90
	v_add_f32_e32 v233, v128, v129
	v_exp_f32_e32 v131, v91
	v_cvt_pk_bf16_f32 v186, v128, v129
	s_waitcnt lgkmcnt(4)
	v_mfma_f32_32x32x16_bf16 v[4:19], v[164:167], v[136:139], v[4:19]
	ds_read_b128 v[180:183], v155 offset:0
	ds_read_b128 v[112:115], v155 offset:6656
	v_add_f32_e32 v254, v254, v233
	v_exp_f32_e32 v124, v92
	v_add_f32_e32 v224, v130, v131
	v_exp_f32_e32 v125, v93
	v_mfma_f32_32x32x16_bf16 v[20:35], v[168:171], v[136:139], v[20:35]
	ds_read_b128 v[116:119], v155 offset:32
	ds_read_b128 v[120:123], v155 offset:6688
	v_cvt_pk_bf16_f32 v187, v130, v131
	v_add_f32_e32 v254, v254, v224
	v_exp_f32_e32 v126, v94
	v_add_f32_e32 v226, v124, v125
	s_waitcnt lgkmcnt(4)
	v_mfma_f32_32x32x16_bf16 v[4:19], v[172:175], v[132:135], v[4:19]
	v_exp_f32_e32 v127, v95
	v_cvt_pk_bf16_f32 v188, v124, v125
	v_add_f32_e32 v254, v254, v226
	v_exp_f32_e32 v128, v96
	v_mfma_f32_32x32x16_bf16 v[20:35], v[176:179], v[132:135], v[20:35]
	v_add_f32_e32 v233, v126, v127
	v_exp_f32_e32 v129, v97
	v_cvt_pk_bf16_f32 v189, v126, v127
	v_add_f32_e32 v254, v254, v233
	s_waitcnt lgkmcnt(2)
	v_mfma_f32_32x32x16_bf16 v[52:67], v[180:183], v[200:203], v[234:249]
	ds_read_b128 v[180:183], v155 offset:64
	v_exp_f32_e32 v130, v98
	v_add_f32_e32 v224, v128, v129
	v_exp_f32_e32 v131, v99
	v_cvt_pk_bf16_f32 v190, v128, v129
	v_mfma_f32_32x32x16_bf16 v[68:83], v[112:115], v[200:203], v[234:249]
	s_barrier
	s_waitcnt vmcnt(0)
	ds_write_b128 v157, v[104:107] offset:13312
	ds_write_b64 v158, v[108:109] offset:13440
	ds_write_b128 v151, v[100:103] offset:38912
	buffer_load_dwordx2 v[108:109], v161, s[12:15], s52 offen
	s_add_i32 s3, s53, 0xfe040000
	buffer_load_dwordx4 v[104:107], v150, s[12:15], s3 offen
	buffer_load_dwordx4 v[100:103], v150, s[12:15], s53 offen
	ds_read_b128 v[112:115], v155 offset:6720
	v_add_f32_e32 v254, v254, v224
	v_exp_f32_e32 v124, v36
	v_add_f32_e32 v226, v130, v131
	v_exp_f32_e32 v125, v37
	s_waitcnt lgkmcnt(5)
	v_mfma_f32_32x32x16_bf16 v[52:67], v[116:119], v[204:207], v[52:67]
	ds_read_b128 v[116:119], v155 offset:96
	v_cvt_pk_bf16_f32 v191, v130, v131
	v_add_f32_e32 v254, v254, v226
	v_exp_f32_e32 v126, v38
	v_add_f32_e32 v233, v124, v125
	v_mfma_f32_32x32x16_bf16 v[68:83], v[120:123], v[204:207], v[68:83]
	ds_read_b128 v[120:123], v155 offset:6752
	v_exp_f32_e32 v127, v39
	v_cvt_pk_bf16_f32 v192, v124, v125
	v_add_f32_e32 v254, v254, v233
	v_exp_f32_e32 v128, v40
	s_waitcnt lgkmcnt(2)
	v_mfma_f32_32x32x16_bf16 v[52:67], v[180:183], v[208:211], v[52:67]
	s_barrier
	ds_read_b128 v[180:183], v155 offset:128
	v_add_f32_e32 v224, v126, v127
	v_exp_f32_e32 v129, v41
	v_cvt_pk_bf16_f32 v193, v126, v127
	v_add_f32_e32 v254, v254, v224
	v_mfma_f32_32x32x16_bf16 v[68:83], v[112:115], v[208:211], v[68:83]
	ds_read_b128 v[112:115], v155 offset:6784
	v_exp_f32_e32 v130, v42
	v_add_f32_e32 v226, v128, v129
	v_exp_f32_e32 v131, v43
	v_cvt_pk_bf16_f32 v194, v128, v129
	s_waitcnt lgkmcnt(2)
	v_mfma_f32_32x32x16_bf16 v[52:67], v[116:119], v[212:215], v[52:67]
	ds_read_b128 v[116:119], v155 offset:160
	v_add_f32_e32 v254, v254, v226
	v_exp_f32_e32 v124, v44
	v_add_f32_e32 v233, v130, v131
	v_exp_f32_e32 v125, v45
	v_mfma_f32_32x32x16_bf16 v[68:83], v[120:123], v[212:215], v[68:83]
	ds_read_b128 v[120:123], v155 offset:6816
	v_cvt_pk_bf16_f32 v195, v130, v131
	v_add_f32_e32 v254, v254, v233
	v_exp_f32_e32 v126, v46
	v_add_f32_e32 v224, v124, v125
	s_waitcnt lgkmcnt(2)
	v_mfma_f32_32x32x16_bf16 v[52:67], v[180:183], v[216:219], v[52:67]
	v_exp_f32_e32 v127, v47
	v_cvt_pk_bf16_f32 v196, v124, v125
	v_add_f32_e32 v254, v254, v224
	v_exp_f32_e32 v128, v48
	v_mfma_f32_32x32x16_bf16 v[68:83], v[112:115], v[216:219], v[68:83]
	v_add_f32_e32 v226, v126, v127
	v_exp_f32_e32 v129, v49
	v_cvt_pk_bf16_f32 v197, v126, v127
	v_add_f32_e32 v254, v254, v226
	s_waitcnt lgkmcnt(0)
	v_mfma_f32_32x32x16_bf16 v[52:67], v[116:119], v[250:253], v[52:67]
	v_exp_f32_e32 v130, v50
	v_add_f32_e32 v233, v128, v129
	v_exp_f32_e32 v131, v51
	v_cvt_pk_bf16_f32 v198, v128, v129
	v_mfma_f32_32x32x16_bf16 v[68:83], v[120:123], v[250:253], v[68:83]
	v_add_f32_e32 v254, v254, v233
	v_add_f32_e32 v224, v130, v131
	v_cvt_pk_bf16_f32 v199, v130, v131
	v_add_f32_e32 v254, v254, v224
	ds_read_b64_tr_b16 v[164:165], v162 offset:38912
	ds_read_b64_tr_b16 v[166:167], v162 offset:40448
	ds_read_b64_tr_b16 v[168:169], v162 offset:38976
	ds_read_b64_tr_b16 v[170:171], v162 offset:40512
	ds_read_b64_tr_b16 v[172:173], v162 offset:41984
	ds_read_b64_tr_b16 v[174:175], v162 offset:43520
	v_cmp_lt_f32_e32 vcc, 0x43800000, v254
	s_cbranch_vccnz .LpfU_s0

.LpfU_nr0:
	s_mov_b32 s5, 0
	s_waitcnt lgkmcnt(2)
	v_mfma_f32_32x32x16_bf16 v[4:19], v[164:167], v[184:187], v[4:19]
	ds_read_b64_tr_b16 v[176:177], v162 offset:42048
	ds_read_b64_tr_b16 v[178:179], v162 offset:43584
	ds_read_b64_tr_b16 v[164:165], v162 offset:45056
	ds_read_b64_tr_b16 v[166:167], v162 offset:46592
	v_exp_f32_e32 v124, v52
	v_exp_f32_e32 v125, v53
	v_exp_f32_e32 v126, v54
	v_add_f32_e32 v224, v124, v125
	v_mfma_f32_32x32x16_bf16 v[20:35], v[168:171], v[184:187], v[20:35]
	ds_read_b64_tr_b16 v[168:169], v162 offset:45120
	ds_read_b64_tr_b16 v[170:171], v162 offset:46656
	v_exp_f32_e32 v127, v55
	v_cvt_pk_bf16_f32 v144, v124, v125
	v_mov_b32_e32 v254, v224
	v_exp_f32_e32 v128, v56
	s_waitcnt lgkmcnt(4)
	v_mfma_f32_32x32x16_bf16 v[4:19], v[172:175], v[188:191], v[4:19]
	ds_read_b64_tr_b16 v[172:173], v162 offset:48128
	ds_read_b64_tr_b16 v[174:175], v162 offset:49664
	v_add_f32_e32 v226, v126, v127
	v_exp_f32_e32 v129, v57
	v_cvt_pk_bf16_f32 v145, v126, v127
	v_add_f32_e32 v254, v254, v226
	v_mfma_f32_32x32x16_bf16 v[20:35], v[176:179], v[188:191], v[20:35]
	ds_read_b64_tr_b16 v[176:177], v162 offset:48192
	ds_read_b64_tr_b16 v[178:179], v162 offset:49728
	v_exp_f32_e32 v130, v58
	v_add_f32_e32 v233, v128, v129
	v_exp_f32_e32 v131, v59
	v_cvt_pk_bf16_f32 v146, v128, v129
	s_waitcnt lgkmcnt(4)
	v_mfma_f32_32x32x16_bf16 v[4:19], v[164:167], v[192:195], v[4:19]
	ds_read_b128 v[180:183], v155 offset:13312
	ds_read_b128 v[112:115], v155 offset:19968
	v_add_f32_e32 v254, v254, v233
	v_exp_f32_e32 v124, v60
	v_add_f32_e32 v224, v130, v131
	v_exp_f32_e32 v125, v61
	v_mfma_f32_32x32x16_bf16 v[20:35], v[168:171], v[192:195], v[20:35]
	ds_read_b128 v[116:119], v155 offset:13344
	ds_read_b128 v[120:123], v155 offset:20000
	v_cvt_pk_bf16_f32 v147, v130, v131
	v_add_f32_e32 v254, v254, v224
	v_exp_f32_e32 v126, v62
	v_add_f32_e32 v226, v124, v125
	s_waitcnt lgkmcnt(4)
	v_mfma_f32_32x32x16_bf16 v[4:19], v[172:175], v[196:199], v[4:19]
	v_exp_f32_e32 v127, v63
	v_cvt_pk_bf16_f32 v140, v124, v125
	v_add_f32_e32 v254, v254, v226
	v_exp_f32_e32 v128, v64
	v_mfma_f32_32x32x16_bf16 v[20:35], v[176:179], v[196:199], v[20:35]
	v_add_f32_e32 v233, v126, v127
	v_exp_f32_e32 v129, v65
	v_cvt_pk_bf16_f32 v141, v126, v127
	v_add_f32_e32 v254, v254, v233
	s_waitcnt lgkmcnt(2)
	v_mfma_f32_32x32x16_bf16 v[84:99], v[180:183], v[200:203], v[234:249]
	ds_read_b128 v[180:183], v155 offset:13376
	v_exp_f32_e32 v130, v66
	v_add_f32_e32 v224, v128, v129
	v_exp_f32_e32 v131, v67
	v_cvt_pk_bf16_f32 v142, v128, v129
	v_mfma_f32_32x32x16_bf16 v[36:51], v[112:115], v[200:203], v[234:249]
	s_barrier
	s_waitcnt vmcnt(0)
	ds_write_b128 v157, v[104:107]
	ds_write_b64 v158, v[108:109] offset:128
	ds_write_b128 v151, v[100:103] offset:26624
	s_add_i32 s2, s51, 2
	s_cmp_lt_i32 s2, s50
	s_cbranch_scc0 .LpfU_nl
	s_add_i32 s2, s52, 0x1000
	buffer_load_dwordx2 v[108:109], v161, s[12:15], s2 offen
	s_add_i32 s3, s53, 0xfe060000
	buffer_load_dwordx4 v[104:107], v150, s[12:15], s3 offen
	s_add_i32 s4, s53, 0x20000
	buffer_load_dwordx4 v[100:103], v150, s[12:15], s4 offen
.LpfU_nl:
	ds_read_b128 v[112:115], v155 offset:20032
	v_add_f32_e32 v254, v254, v224
	v_exp_f32_e32 v124, v68
	v_add_f32_e32 v226, v130, v131
	v_exp_f32_e32 v125, v69
	s_waitcnt lgkmcnt(5)
	v_mfma_f32_32x32x16_bf16 v[84:99], v[116:119], v[204:207], v[84:99]
	ds_read_b128 v[116:119], v155 offset:13408
	v_cvt_pk_bf16_f32 v143, v130, v131
	v_add_f32_e32 v254, v254, v226
	v_exp_f32_e32 v126, v70
	v_add_f32_e32 v233, v124, v125
	v_mfma_f32_32x32x16_bf16 v[36:51], v[120:123], v[204:207], v[36:51]
	ds_read_b128 v[120:123], v155 offset:20064
	v_exp_f32_e32 v127, v71
	v_cvt_pk_bf16_f32 v136, v124, v125
	v_add_f32_e32 v254, v254, v233
	v_exp_f32_e32 v128, v72
	s_waitcnt lgkmcnt(2)
	v_mfma_f32_32x32x16_bf16 v[84:99], v[180:183], v[208:211], v[84:99]
	s_barrier
	ds_read_b128 v[180:183], v155 offset:13440
	v_add_f32_e32 v224, v126, v127
	v_exp_f32_e32 v129, v73
	v_cvt_pk_bf16_f32 v137, v126, v127
	v_add_f32_e32 v254, v254, v224
	v_mfma_f32_32x32x16_bf16 v[36:51], v[112:115], v[208:211], v[36:51]
	ds_read_b128 v[112:115], v155 offset:20096
	v_exp_f32_e32 v130, v74
	v_add_f32_e32 v226, v128, v129
	v_exp_f32_e32 v131, v75
	v_cvt_pk_bf16_f32 v138, v128, v129
	s_waitcnt lgkmcnt(2)
	v_mfma_f32_32x32x16_bf16 v[84:99], v[116:119], v[212:215], v[84:99]
	ds_read_b128 v[116:119], v155 offset:13472
	v_add_f32_e32 v254, v254, v226
	v_exp_f32_e32 v124, v76
	v_add_f32_e32 v233, v130, v131
	v_exp_f32_e32 v125, v77
	v_mfma_f32_32x32x16_bf16 v[36:51], v[120:123], v[212:215], v[36:51]
	ds_read_b128 v[120:123], v155 offset:20128
	v_cvt_pk_bf16_f32 v139, v130, v131
	v_add_f32_e32 v254, v254, v233
	v_exp_f32_e32 v126, v78
	v_add_f32_e32 v224, v124, v125
	s_waitcnt lgkmcnt(2)
	v_mfma_f32_32x32x16_bf16 v[84:99], v[180:183], v[216:219], v[84:99]
	v_exp_f32_e32 v127, v79
	v_cvt_pk_bf16_f32 v132, v124, v125
	v_add_f32_e32 v254, v254, v224
	v_exp_f32_e32 v128, v80
	v_mfma_f32_32x32x16_bf16 v[36:51], v[112:115], v[216:219], v[36:51]
	v_add_f32_e32 v226, v126, v127
	v_exp_f32_e32 v129, v81
	v_cvt_pk_bf16_f32 v133, v126, v127
	v_add_f32_e32 v254, v254, v226
	s_waitcnt lgkmcnt(0)
	v_mfma_f32_32x32x16_bf16 v[84:99], v[116:119], v[250:253], v[84:99]
	v_exp_f32_e32 v130, v82
	v_add_f32_e32 v233, v128, v129
	v_exp_f32_e32 v131, v83
	v_cvt_pk_bf16_f32 v134, v128, v129
	v_mfma_f32_32x32x16_bf16 v[36:51], v[120:123], v[250:253], v[36:51]
	v_add_f32_e32 v254, v254, v233
	v_add_f32_e32 v224, v130, v131
	v_cvt_pk_bf16_f32 v135, v130, v131
	v_add_f32_e32 v254, v254, v224
	ds_read_b64_tr_b16 v[164:165], v162 offset:26624
	ds_read_b64_tr_b16 v[166:167], v162 offset:28160
	ds_read_b64_tr_b16 v[168:169], v162 offset:26688
	ds_read_b64_tr_b16 v[170:171], v162 offset:28224
	ds_read_b64_tr_b16 v[172:173], v162 offset:29696
	ds_read_b64_tr_b16 v[174:175], v162 offset:31232
	v_cmp_lt_f32_e32 vcc, 0x43800000, v254
	s_cbranch_vccnz .LpfU_s1
